# v24
# speedup vs baseline: 1.0184x; 1.0026x over previous
.LBB0_63:
	s_sleep 12
	global_load_dword v2, v0, s[6:7] offset:32 sc1
	s_waitcnt vmcnt(0)
	v_and_b32_e32 v2, 0xffff0000, v2
	v_cmp_ne_u32_e32 vcc, v2, v1
	s_or_b64 s[8:9], vcc, s[8:9]
	s_andn2_b64 exec, exec, s[8:9]
	s_cbranch_execnz .LBB0_63

.LBB0_266:
	s_sleep 12
	global_load_dword v2, v0, s[6:7] offset:32 sc1
	s_waitcnt vmcnt(0)
	v_and_b32_e32 v2, 0xffff0000, v2
	v_cmp_ne_u32_e32 vcc, v2, v1
	s_or_b64 s[10:11], vcc, s[10:11]
	s_andn2_b64 exec, exec, s[10:11]
	s_cbranch_execnz .LBB0_266

.LBB0_379:
	s_sleep 12
	global_load_dword v2, v0, s[0:1] offset:32 sc1
	s_waitcnt vmcnt(0)
	v_and_b32_e32 v2, 0xffff0000, v2
	v_cmp_ne_u32_e32 vcc, v2, v1
	s_or_b64 s[4:5], vcc, s[4:5]
	s_andn2_b64 exec, exec, s[4:5]
	s_cbranch_execnz .LBB0_379
